# S5 epilogue: second bf16 residual batch issued with the first (vmcnt(8)/vmcnt(12)), on top of the same change in S7
# baseline (speedup 1.0000x reference)
.LBB0_1335:
	v_lshl_add_u32 v168, s30, 8, v188
	v_lshl_add_u32 v172, s28, 8, v186
	v_ashrrev_i32_e32 v169, 31, v168
	v_lshlrev_b64 v[202:203], 1, v[168:169]
	v_ashrrev_i32_e32 v173, 31, v172
	v_lshl_add_u64 v[170:171], s[12:13], 0, v[202:203]
	v_lshlrev_b64 v[204:205], 12, v[172:173]
	v_lshl_add_u64 v[128:129], v[170:171], 0, v[204:205]
	global_load_dwordx4 v[194:197], v[128:129], off
	global_load_dwordx4 v[198:201], v[128:129], off offset:256
	v_or_b32_e32 v182, 16, v172
	v_or_b32_e32 v178, 32, v172
	v_or_b32_e32 v174, 48, v172
	v_ashrrev_i32_e32 v183, 31, v182
	v_ashrrev_i32_e32 v179, 31, v178
	v_ashrrev_i32_e32 v175, 31, v174
	v_lshlrev_b64 v[184:185], 12, v[182:183]
	v_lshlrev_b64 v[180:181], 12, v[178:179]
	v_lshlrev_b64 v[176:177], 12, v[174:175]
	v_lshl_add_u64 v[128:129], v[170:171], 0, v[184:185]
	v_lshl_add_u64 v[130:131], v[170:171], 0, v[180:181]
	v_lshl_add_u64 v[206:207], v[170:171], 0, v[176:177]
	global_load_dwordx4 v[148:151], v[128:129], off
	global_load_dwordx4 v[144:147], v[128:129], off offset:256
	global_load_dwordx4 v[140:143], v[130:131], off
	global_load_dwordx4 v[136:139], v[130:131], off offset:256
	global_load_dwordx4 v[132:135], v[206:207], off
	s_nop 0
	global_load_dwordx4 v[128:131], v[206:207], off offset:256
	v_add_u32_e32 v222, 0x80, v172
	v_ashrrev_i32_e32 v223, 31, v222
	v_lshlrev_b64 v[222:223], 12, v[222:223]
	v_lshl_add_u64 v[222:223], v[170:171], 0, v[222:223]
	global_load_dwordx4 v[226:229], v[222:223], off
	global_load_dwordx4 v[230:233], v[222:223], off offset:256
	v_add_u32_e32 v222, 0x90, v172
	v_ashrrev_i32_e32 v223, 31, v222
	v_lshlrev_b64 v[222:223], 12, v[222:223]
	v_lshl_add_u64 v[222:223], v[170:171], 0, v[222:223]
	global_load_dwordx4 v[234:237], v[222:223], off
	global_load_dwordx4 v[238:241], v[222:223], off offset:256
	v_add_u32_e32 v222, 0xa0, v172
	v_ashrrev_i32_e32 v223, 31, v222
	v_lshlrev_b64 v[222:223], 12, v[222:223]
	v_lshl_add_u64 v[222:223], v[170:171], 0, v[222:223]
	global_load_dwordx4 v[242:245], v[222:223], off
	global_load_dwordx4 v[246:249], v[222:223], off offset:256
	v_add_u32_e32 v222, 0xb0, v172
	v_ashrrev_i32_e32 v223, 31, v222
	v_lshlrev_b64 v[222:223], 12, v[222:223]
	v_lshl_add_u64 v[222:223], v[170:171], 0, v[222:223]
	global_load_dwordx4 v[250:253], v[222:223], off
	global_load_dwordx4 v[218:221], v[222:223], off offset:256
	v_and_b32_e32 v206, 64, v192
	v_xor_b32_e32 v193, 16, v192
	v_add_u32_e32 v206, 64, v206
	v_xor_b32_e32 v207, 32, v192
	v_cmp_lt_i32_e32 vcc, v193, v206
	v_lshl_add_u64 v[204:205], s[16:17], 0, v[204:205]
	v_lshl_add_u64 v[202:203], v[204:205], 0, v[202:203]
	v_cndmask_b32_e32 v193, v192, v193, vcc
	v_cmp_lt_i32_e32 vcc, v207, v206
	v_lshlrev_b32_e32 v193, 2, v193
	s_waitcnt vmcnt(8) lgkmcnt(0)
	v_lshlrev_b32_e32 v204, 16, v194
	v_cndmask_b32_e32 v212, v192, v207, vcc
	v_and_b32_e32 v205, 0xffff0000, v194
	v_lshlrev_b32_e32 v194, 16, v195
	v_and_b32_e32 v195, 0xffff0000, v195
	v_lshlrev_b32_e32 v206, 16, v196
	v_and_b32_e32 v207, 0xffff0000, v196
	v_lshlrev_b32_e32 v196, 16, v197
	v_and_b32_e32 v197, 0xffff0000, v197
	v_lshlrev_b32_e32 v208, 16, v198
	v_and_b32_e32 v209, 0xffff0000, v198
	v_lshlrev_b32_e32 v198, 16, v199
	v_and_b32_e32 v199, 0xffff0000, v199
	v_lshlrev_b32_e32 v210, 16, v200
	v_and_b32_e32 v211, 0xffff0000, v200
	v_lshlrev_b32_e32 v200, 16, v201
	v_and_b32_e32 v201, 0xffff0000, v201
	v_pk_add_f32 v[126:127], v[126:127], v[194:195]
	v_pk_add_f32 v[124:125], v[124:125], v[204:205]
	v_pk_add_f32 v[122:123], v[122:123], v[196:197]
	v_pk_add_f32 v[120:121], v[120:121], v[206:207]
	v_pk_add_f32 v[118:119], v[118:119], v[198:199]
	v_pk_add_f32 v[116:117], v[116:117], v[208:209]
	v_pk_add_f32 v[194:195], v[114:115], v[200:201]
	v_pk_add_f32 v[196:197], v[112:113], v[210:211]
	v_cvt_pk_bf16_f32 v112, v124, v125
	v_cvt_pk_bf16_f32 v113, v126, v127
	v_mul_f32_e32 v114, v125, v125
	v_mul_f32_e32 v115, v127, v127
	v_mul_f32_e32 v125, v121, v121
	v_mul_f32_e32 v127, v123, v123
	v_mul_f32_e32 v198, v117, v117
	v_mul_f32_e32 v199, v119, v119
	v_mul_f32_e32 v200, v197, v197
	v_mul_f32_e32 v201, v195, v195
	v_fmac_f32_e32 v114, v124, v124
	v_fmac_f32_e32 v115, v126, v126
	v_fmac_f32_e32 v125, v120, v120
	v_fmac_f32_e32 v127, v122, v122
	v_fmac_f32_e32 v198, v116, v116
	v_fmac_f32_e32 v199, v118, v118
	v_fmac_f32_e32 v200, v196, v196
	v_fmac_f32_e32 v201, v194, v194
	v_add_f32_e32 v114, v114, v115
	v_add_f32_e32 v115, v125, v127
	v_add_f32_e32 v124, v198, v199
	v_add_f32_e32 v125, v200, v201
	v_add_f32_e32 v114, v114, v115
	v_add_f32_e32 v115, v124, v125
	v_add_f32_e32 v124, v114, v115
	ds_bpermute_b32 v125, v193, v124
	v_cvt_pk_bf16_f32 v114, v120, v121
	v_cvt_pk_bf16_f32 v115, v122, v123
	global_store_dwordx4 v[202:203], v[112:115], off
	v_cvt_pk_bf16_f32 v116, v116, v117
	v_cvt_pk_bf16_f32 v117, v118, v119
	v_cvt_pk_bf16_f32 v118, v196, v197
	v_cvt_pk_bf16_f32 v119, v194, v195
	global_store_dwordx4 v[202:203], v[116:119], off offset:256
	s_waitcnt lgkmcnt(0)
	v_add_f32_e32 v113, v124, v125
	v_lshlrev_b32_e32 v112, 2, v212
	ds_bpermute_b32 v114, v112, v113
	s_and_saveexec_b64 s[4:5], s[6:7]
	s_nop 0
	s_waitcnt lgkmcnt(0)
	v_add_f32_e32 v113, v113, v114
	v_lshl_add_u64 v[114:115], v[172:173], 2, s[10:11]
	global_atomic_add_f32 v[114:115], v113, off
.LBB0_1337:
	s_or_b64 exec, exec, s[4:5]
	s_waitcnt lgkmcnt(0)
	v_lshlrev_b32_e32 v114, 16, v148
	v_and_b32_e32 v115, 0xffff0000, v148
	v_lshlrev_b32_e32 v116, 16, v149
	v_and_b32_e32 v117, 0xffff0000, v149
	v_lshlrev_b32_e32 v118, 16, v150
	v_and_b32_e32 v119, 0xffff0000, v150
	v_pk_add_f32 v[108:109], v[108:109], v[114:115]
	v_pk_add_f32 v[110:111], v[110:111], v[116:117]
	v_pk_add_f32 v[116:117], v[104:105], v[118:119]
	v_cvt_pk_bf16_f32 v104, v108, v109
	v_mul_f32_e32 v109, v109, v109
	v_lshlrev_b32_e32 v120, 16, v151
	v_and_b32_e32 v121, 0xffff0000, v151
	v_fmac_f32_e32 v109, v108, v108
	v_mul_f32_e32 v108, v111, v111
	v_pk_add_f32 v[114:115], v[106:107], v[120:121]
	v_fmac_f32_e32 v108, v110, v110
	v_cvt_pk_bf16_f32 v105, v110, v111
	v_add_f32_e32 v108, v109, v108
	v_mul_f32_e32 v109, v117, v117
	v_mul_f32_e32 v110, v115, v115
	v_fmac_f32_e32 v109, v116, v116
	v_fmac_f32_e32 v110, v114, v114
	v_add_f32_e32 v109, v109, v110
	v_add_f32_e32 v113, v108, v109
	v_lshlrev_b32_e32 v108, 16, v144
	v_and_b32_e32 v109, 0xffff0000, v144
	v_lshlrev_b32_e32 v110, 16, v145
	v_and_b32_e32 v111, 0xffff0000, v145
	v_cvt_pk_bf16_f32 v106, v116, v117
	v_cvt_pk_bf16_f32 v107, v114, v115
	v_lshlrev_b32_e32 v114, 16, v146
	v_and_b32_e32 v115, 0xffff0000, v146
	v_pk_add_f32 v[102:103], v[102:103], v[110:111]
	v_pk_add_f32 v[100:101], v[100:101], v[108:109]
	v_lshlrev_b32_e32 v116, 16, v147
	v_and_b32_e32 v117, 0xffff0000, v147
	v_pk_add_f32 v[110:111], v[96:97], v[114:115]
	v_mul_f32_e32 v96, v101, v101
	v_mul_f32_e32 v97, v103, v103
	v_pk_add_f32 v[108:109], v[98:99], v[116:117]
	v_fmac_f32_e32 v96, v100, v100
	v_fmac_f32_e32 v97, v102, v102
	v_add_f32_e32 v96, v96, v97
	v_mul_f32_e32 v97, v111, v111
	v_mul_f32_e32 v98, v109, v109
	v_fmac_f32_e32 v97, v110, v110
	v_fmac_f32_e32 v98, v108, v108
	v_add_f32_e32 v97, v97, v98
	v_add_f32_e32 v96, v96, v97
	v_add_f32_e32 v99, v113, v96
	ds_bpermute_b32 v113, v193, v99
	v_lshl_add_u64 v[96:97], s[16:17], 0, v[184:185]
	v_lshl_add_u64 v[114:115], v[168:169], 1, v[96:97]
	global_store_dwordx4 v[114:115], v[104:107], off
	v_cvt_pk_bf16_f32 v98, v100, v101
	s_waitcnt lgkmcnt(0)
	v_add_f32_e32 v96, v99, v113
	ds_bpermute_b32 v97, v112, v96
	v_cvt_pk_bf16_f32 v99, v102, v103
	v_cvt_pk_bf16_f32 v100, v110, v111
	v_cvt_pk_bf16_f32 v101, v108, v109
	global_store_dwordx4 v[114:115], v[98:101], off offset:256
	s_and_saveexec_b64 s[4:5], s[6:7]
	s_nop 0
	s_waitcnt lgkmcnt(0)
	v_add_f32_e32 v98, v96, v97
	v_lshl_add_u64 v[96:97], v[182:183], 2, s[10:11]
	global_atomic_add_f32 v[96:97], v98, off
.LBB0_1339:
	s_or_b64 exec, exec, s[4:5]
	v_lshlrev_b32_e32 v96, 16, v140
	s_waitcnt lgkmcnt(0)
	v_and_b32_e32 v97, 0xffff0000, v140
	v_lshlrev_b32_e32 v98, 16, v141
	v_and_b32_e32 v99, 0xffff0000, v141
	v_lshlrev_b32_e32 v100, 16, v142
	v_and_b32_e32 v101, 0xffff0000, v142
	v_pk_add_f32 v[92:93], v[92:93], v[96:97]
	v_pk_add_f32 v[94:95], v[94:95], v[98:99]
	v_pk_add_f32 v[98:99], v[88:89], v[100:101]
	v_cvt_pk_bf16_f32 v88, v92, v93
	v_mul_f32_e32 v93, v93, v93
	v_lshlrev_b32_e32 v102, 16, v143
	v_and_b32_e32 v103, 0xffff0000, v143
	v_fmac_f32_e32 v93, v92, v92
	v_mul_f32_e32 v92, v95, v95
	v_pk_add_f32 v[96:97], v[90:91], v[102:103]
	v_fmac_f32_e32 v92, v94, v94
	v_cvt_pk_bf16_f32 v89, v94, v95
	v_add_f32_e32 v92, v93, v92
	v_mul_f32_e32 v93, v99, v99
	v_mul_f32_e32 v94, v97, v97
	v_fmac_f32_e32 v93, v98, v98
	v_fmac_f32_e32 v94, v96, v96
	v_add_f32_e32 v93, v93, v94
	v_add_f32_e32 v100, v92, v93
	v_lshlrev_b32_e32 v92, 16, v136
	v_and_b32_e32 v93, 0xffff0000, v136
	v_lshlrev_b32_e32 v94, 16, v137
	v_and_b32_e32 v95, 0xffff0000, v137
	v_cvt_pk_bf16_f32 v90, v98, v99
	v_cvt_pk_bf16_f32 v91, v96, v97
	v_lshlrev_b32_e32 v96, 16, v138
	v_and_b32_e32 v97, 0xffff0000, v138
	v_pk_add_f32 v[86:87], v[86:87], v[94:95]
	v_pk_add_f32 v[84:85], v[84:85], v[92:93]
	v_lshlrev_b32_e32 v98, 16, v139
	v_and_b32_e32 v99, 0xffff0000, v139
	v_pk_add_f32 v[94:95], v[80:81], v[96:97]
	v_mul_f32_e32 v80, v85, v85
	v_mul_f32_e32 v81, v87, v87
	v_pk_add_f32 v[92:93], v[82:83], v[98:99]
	v_fmac_f32_e32 v80, v84, v84
	v_fmac_f32_e32 v81, v86, v86
	v_add_f32_e32 v80, v80, v81
	v_mul_f32_e32 v81, v95, v95
	v_mul_f32_e32 v82, v93, v93
	v_fmac_f32_e32 v81, v94, v94
	v_fmac_f32_e32 v82, v92, v92
	v_add_f32_e32 v81, v81, v82
	v_add_f32_e32 v80, v80, v81
	v_add_f32_e32 v83, v100, v80
	ds_bpermute_b32 v98, v193, v83
	v_lshl_add_u64 v[80:81], s[16:17], 0, v[180:181]
	v_lshl_add_u64 v[96:97], v[168:169], 1, v[80:81]
	global_store_dwordx4 v[96:97], v[88:91], off
	v_cvt_pk_bf16_f32 v82, v84, v85
	s_waitcnt lgkmcnt(0)
	v_add_f32_e32 v80, v83, v98
	ds_bpermute_b32 v81, v112, v80
	v_cvt_pk_bf16_f32 v83, v86, v87
	v_cvt_pk_bf16_f32 v84, v94, v95
	v_cvt_pk_bf16_f32 v85, v92, v93
	global_store_dwordx4 v[96:97], v[82:85], off offset:256
	s_and_saveexec_b64 s[4:5], s[6:7]
	s_nop 0
	s_waitcnt lgkmcnt(0)
	v_add_f32_e32 v82, v80, v81
	v_lshl_add_u64 v[80:81], v[178:179], 2, s[10:11]
	global_atomic_add_f32 v[80:81], v82, off
.LBB0_1341:
	s_or_b64 exec, exec, s[4:5]
	v_lshlrev_b32_e32 v80, 16, v132
	s_waitcnt lgkmcnt(0)
	v_and_b32_e32 v81, 0xffff0000, v132
	v_lshlrev_b32_e32 v82, 16, v133
	v_and_b32_e32 v83, 0xffff0000, v133
	v_lshlrev_b32_e32 v84, 16, v134
	v_and_b32_e32 v85, 0xffff0000, v134
	v_pk_add_f32 v[76:77], v[76:77], v[80:81]
	v_pk_add_f32 v[78:79], v[78:79], v[82:83]
	v_pk_add_f32 v[82:83], v[72:73], v[84:85]
	v_cvt_pk_bf16_f32 v72, v76, v77
	v_mul_f32_e32 v77, v77, v77
	v_lshlrev_b32_e32 v86, 16, v135
	v_and_b32_e32 v87, 0xffff0000, v135
	v_fmac_f32_e32 v77, v76, v76
	v_mul_f32_e32 v76, v79, v79
	v_pk_add_f32 v[80:81], v[74:75], v[86:87]
	v_fmac_f32_e32 v76, v78, v78
	v_cvt_pk_bf16_f32 v73, v78, v79
	v_add_f32_e32 v76, v77, v76
	v_mul_f32_e32 v77, v83, v83
	v_mul_f32_e32 v78, v81, v81
	v_fmac_f32_e32 v77, v82, v82
	v_fmac_f32_e32 v78, v80, v80
	v_add_f32_e32 v77, v77, v78
	v_add_f32_e32 v84, v76, v77
	v_lshlrev_b32_e32 v76, 16, v128
	v_and_b32_e32 v77, 0xffff0000, v128
	v_lshlrev_b32_e32 v78, 16, v129
	v_and_b32_e32 v79, 0xffff0000, v129
	v_cvt_pk_bf16_f32 v74, v82, v83
	v_cvt_pk_bf16_f32 v75, v80, v81
	v_lshlrev_b32_e32 v80, 16, v130
	v_and_b32_e32 v81, 0xffff0000, v130
	v_pk_add_f32 v[70:71], v[70:71], v[78:79]
	v_pk_add_f32 v[68:69], v[68:69], v[76:77]
	v_lshlrev_b32_e32 v82, 16, v131
	v_and_b32_e32 v83, 0xffff0000, v131
	v_pk_add_f32 v[78:79], v[64:65], v[80:81]
	v_mul_f32_e32 v64, v69, v69
	v_mul_f32_e32 v65, v71, v71
	v_pk_add_f32 v[76:77], v[66:67], v[82:83]
	v_fmac_f32_e32 v64, v68, v68
	v_fmac_f32_e32 v65, v70, v70
	v_add_f32_e32 v64, v64, v65
	v_mul_f32_e32 v65, v79, v79
	v_mul_f32_e32 v66, v77, v77
	v_fmac_f32_e32 v65, v78, v78
	v_fmac_f32_e32 v66, v76, v76
	v_add_f32_e32 v65, v65, v66
	v_add_f32_e32 v64, v64, v65
	v_add_f32_e32 v67, v84, v64
	ds_bpermute_b32 v82, v193, v67
	v_lshl_add_u64 v[64:65], s[16:17], 0, v[176:177]
	v_lshl_add_u64 v[80:81], v[168:169], 1, v[64:65]
	global_store_dwordx4 v[80:81], v[72:75], off
	v_cvt_pk_bf16_f32 v66, v68, v69
	s_waitcnt lgkmcnt(0)
	v_add_f32_e32 v64, v67, v82
	ds_bpermute_b32 v65, v112, v64
	v_cvt_pk_bf16_f32 v67, v70, v71
	v_cvt_pk_bf16_f32 v68, v78, v79
	v_cvt_pk_bf16_f32 v69, v76, v77
	global_store_dwordx4 v[80:81], v[66:69], off offset:256
	s_and_saveexec_b64 s[4:5], s[6:7]
	s_nop 0
	s_waitcnt lgkmcnt(0)
	v_add_f32_e32 v66, v64, v65
	v_lshl_add_u64 v[64:65], v[174:175], 2, s[10:11]
	global_atomic_add_f32 v[64:65], v66, off
.LBB0_1343:
	s_or_b64 exec, exec, s[4:5]
	v_add_u32_e32 v100, 0x80, v172
	v_ashrrev_i32_e32 v101, 31, v100
	v_lshlrev_b64 v[110:111], 12, v[100:101]
	s_waitcnt lgkmcnt(0)
	v_lshl_add_u64 v[64:65], v[170:171], 0, v[110:111]
	s_waitcnt vmcnt(12)
	v_mov_b64_e32 v[102:103], v[226:227]
	v_mov_b64_e32 v[104:105], v[228:229]
	v_mov_b64_e32 v[106:107], v[230:231]
	v_mov_b64_e32 v[108:109], v[232:233]
	v_add_u32_e32 v96, 0x90, v172
	v_add_u32_e32 v92, 0xa0, v172
	v_add_u32_e32 v88, 0xb0, v172
	v_ashrrev_i32_e32 v97, 31, v96
	v_ashrrev_i32_e32 v93, 31, v92
	v_ashrrev_i32_e32 v89, 31, v88
	v_lshlrev_b64 v[98:99], 12, v[96:97]
	v_lshlrev_b64 v[94:95], 12, v[92:93]
	v_lshlrev_b64 v[90:91], 12, v[88:89]
	v_lshl_add_u64 v[64:65], v[170:171], 0, v[98:99]
	v_lshl_add_u64 v[66:67], v[170:171], 0, v[94:95]
	v_lshl_add_u64 v[114:115], v[170:171], 0, v[90:91]
	v_mov_b64_e32 v[84:85], v[234:235]
	v_mov_b64_e32 v[86:87], v[236:237]
	v_mov_b64_e32 v[80:81], v[238:239]
	v_mov_b64_e32 v[82:83], v[240:241]
	v_mov_b64_e32 v[76:77], v[242:243]
	v_mov_b64_e32 v[78:79], v[244:245]
	v_mov_b64_e32 v[72:73], v[246:247]
	v_mov_b64_e32 v[74:75], v[248:249]
	v_mov_b64_e32 v[68:69], v[250:251]
	v_mov_b64_e32 v[70:71], v[252:253]
	s_nop 0
	v_mov_b64_e32 v[64:65], v[218:219]
	v_mov_b64_e32 v[66:67], v[220:221]
	s_waitcnt lgkmcnt(0)
	v_lshlrev_b32_e32 v114, 16, v102
	v_and_b32_e32 v115, 0xffff0000, v102
	v_lshlrev_b32_e32 v102, 16, v103
	v_and_b32_e32 v103, 0xffff0000, v103
	v_lshlrev_b32_e32 v116, 16, v104
	v_and_b32_e32 v117, 0xffff0000, v104
	v_lshlrev_b32_e32 v104, 16, v105
	v_and_b32_e32 v105, 0xffff0000, v105
	v_lshlrev_b32_e32 v118, 16, v106
	v_and_b32_e32 v119, 0xffff0000, v106
	v_lshlrev_b32_e32 v106, 16, v107
	v_and_b32_e32 v107, 0xffff0000, v107
	v_lshlrev_b32_e32 v120, 16, v108
	v_and_b32_e32 v121, 0xffff0000, v108
	v_lshlrev_b32_e32 v108, 16, v109
	v_and_b32_e32 v109, 0xffff0000, v109
	v_pk_add_f32 v[62:63], v[62:63], v[102:103]
	v_pk_add_f32 v[60:61], v[60:61], v[114:115]
	v_pk_add_f32 v[58:59], v[58:59], v[104:105]
	v_pk_add_f32 v[56:57], v[56:57], v[116:117]
	v_pk_add_f32 v[54:55], v[54:55], v[106:107]
	v_pk_add_f32 v[52:53], v[52:53], v[118:119]
	v_pk_add_f32 v[102:103], v[50:51], v[108:109]
	v_pk_add_f32 v[104:105], v[48:49], v[120:121]
	v_cvt_pk_bf16_f32 v48, v60, v61
	v_cvt_pk_bf16_f32 v49, v62, v63
	v_cvt_pk_bf16_f32 v50, v56, v57
	v_cvt_pk_bf16_f32 v51, v58, v59
	v_mul_f32_e32 v61, v61, v61
	v_mul_f32_e32 v63, v63, v63
	v_mul_f32_e32 v57, v57, v57
	v_mul_f32_e32 v59, v59, v59
	v_mul_f32_e32 v106, v53, v53
	v_mul_f32_e32 v107, v55, v55
	v_mul_f32_e32 v108, v105, v105
	v_mul_f32_e32 v109, v103, v103
	v_fmac_f32_e32 v61, v60, v60
	v_fmac_f32_e32 v63, v62, v62
	v_fmac_f32_e32 v57, v56, v56
	v_fmac_f32_e32 v59, v58, v58
	v_fmac_f32_e32 v106, v52, v52
	v_fmac_f32_e32 v107, v54, v54
	v_fmac_f32_e32 v108, v104, v104
	v_fmac_f32_e32 v109, v102, v102
	v_add_f32_e32 v56, v61, v63
	v_add_f32_e32 v57, v57, v59
	v_add_f32_e32 v58, v106, v107
	v_add_f32_e32 v59, v108, v109
	v_add_f32_e32 v56, v56, v57
	v_add_f32_e32 v57, v58, v59
	v_add_f32_e32 v58, v56, v57
	ds_bpermute_b32 v59, v193, v58
	v_lshl_add_u64 v[56:57], s[16:17], 0, v[110:111]
	v_lshl_add_u64 v[56:57], v[168:169], 1, v[56:57]
	global_store_dwordx4 v[56:57], v[48:51], off
	s_waitcnt lgkmcnt(0)
	s_nop 0
	v_add_f32_e32 v48, v58, v59
	ds_bpermute_b32 v49, v112, v48
	v_cvt_pk_bf16_f32 v50, v52, v53
	v_cvt_pk_bf16_f32 v51, v54, v55
	v_cvt_pk_bf16_f32 v52, v104, v105
	v_cvt_pk_bf16_f32 v53, v102, v103
	global_store_dwordx4 v[56:57], v[50:53], off offset:256
	s_and_saveexec_b64 s[4:5], s[6:7]
	s_cbranch_execz .LBB0_1345
	s_waitcnt lgkmcnt(0)
	v_add_f32_e32 v50, v48, v49
	v_lshl_add_u64 v[48:49], v[100:101], 2, s[10:11]
	global_atomic_add_f32 v[48:49], v50, off
